# v51 + two more SwiGLU-epilogue bias reads hoisted above the alignment barrier
# baseline (speedup 1.0000x reference)
; #define PG8_LAS __attribute__((address_space(3)))
; __device__ __forceinline__ unsigned cvt_pk_bf16(float lo, float hi) { unsigned r; asm volatile("v_cvt_pk_bf16_f32 %0, %1, %2" : "=v"(r) : "v"(lo), "v"(hi)); return r; }
; #define PG8_BAR __builtin_amdgcn_s_barrier()
;     __device__ __forceinline__ void operator()(const f32x4 (&acc)[2][2][4][2], const Unit& u, int wr, int wc, int fr, int fq, PG8_LAS unsigned char* sl) const {
;         const int row0 = u.pm * BM + wr * 64 + fr, col0 = u.pn * HALF + wc * 32 + 8 * fq;
;         const PG8_LAS float* sf = (const PG8_LAS float*)sl;
;         f32x4 bw[2][2];
; #pragma unroll
;         for (int bj = 0; bj < 2; ++bj)
; #pragma unroll
;             for (int n = 0; n < 2; ++n) bw[bj][n] = *(const PG8_LAS f32x4*)(sf + 128 + bj * 32 + 8 * fq + 4 * n);
; #pragma unroll
;         for (int ai = 0; ai < 2; ++ai)
; #pragma unroll
;             for (int m = 0; m < 4; ++m) { const int row = row0 + ai * HALF + m * 16; bf16_t* rowp = O + (size_t)row * ldc + col0;
;                 const float rs = __builtin_amdgcn_rsqf(sf[ai * 64 + m * 16 + fr] * (1.0f / 2048.0f) + 1e-6f);
;                 const f32x4 a0 = acc[ai][0][m][0] * rs + bw[0][0], a1 = acc[ai][0][m][1] * rs + bw[0][1], b0 = acc[ai][1][m][0] * rs + bw[1][0], b1 = acc[ai][1][m][1] * rs + bw[1][1];
;                 const f32x2 s0 = silu_mul_pk((f32x2){a0[0], a0[1]}, (f32x2){b0[0], b0[1]}), s1 = silu_mul_pk((f32x2){a0[2], a0[3]}, (f32x2){b0[2], b0[3]});
;                 const f32x2 s2 = silu_mul_pk((f32x2){a1[0], a1[1]}, (f32x2){b1[0], b1[1]}), s3 = silu_mul_pk((f32x2){a1[2], a1[3]}, (f32x2){b1[2], b1[3]});
;                 u32x4 w; w.x = cvt_pk_bf16(s0.x, s0.y); w.y = cvt_pk_bf16(s1.x, s1.y); w.z = cvt_pk_bf16(s2.x, s2.y); w.w = cvt_pk_bf16(s3.x, s3.y);
;                 *(u32x4*)rowp = w; }
; template <class Epi, class Sched, bool ALIGN_EPI = false, bool SP2 = false>
; __device__ __forceinline__ void gemm_phase(PG8_LAS unsigned char* lds, const Gemm g, const Sched& S, const Epi& E, const int tid) {
;     ...
;         if constexpr (ALIGN_EPI) { if (wr == 0) PG8_BAR; }
;         for (int er = 0; er < Epi::REP; ++er) { E(acc, cur, wr, wc, fr, fq, lds + EPI_LDS_OFF + wid * 1024); if (Epi::REP > 1) asm volatile("" ::: "memory"); }
.LBB0_269:
	ds_read_b32 v128, v163
	ds_read_b128 v[144:147], v162 offset:512
	ds_read_b128 v[140:143], v162 offset:528
	ds_read_b128 v[132:135], v162 offset:640
	s_and_b64 vcc, exec, s[12:13]
	s_cbranch_vccz .LBB0_271
	s_barrier
.LBB0_271:
	v_lshl_or_b32 v168, s74, 7, v164
	v_add_u32_e32 v166, s22, v160
	v_ashrrev_i32_e32 v169, 31, v168
	s_waitcnt lgkmcnt(0)
	v_fmamk_f32 v128, v128, 0x3a000000, v233
	v_rsq_f32_e32 v170, v128
	ds_read_b128 v[128:131], v162 offset:656
	s_andn2_b64 vcc, exec, s[6:7]
	s_mov_b64 s[6:7], -1
	v_pk_fma_f32 v[138:139], v[138:139], v[170:171], v[146:147] op_sel_hi:[1,0,1]
	v_pk_fma_f32 v[136:137], v[136:137], v[170:171], v[144:145] op_sel_hi:[1,0,1]
	s_waitcnt lgkmcnt(0)
	v_pk_fma_f32 v[126:127], v[126:127], v[170:171], v[142:143] op_sel_hi:[1,0,1]
	v_pk_fma_f32 v[122:123], v[122:123], v[170:171], v[134:135] op_sel_hi:[1,0,1]
	v_pk_fma_f32 v[124:125], v[124:125], v[170:171], v[140:141] op_sel_hi:[1,0,1]
	v_pk_fma_f32 v[120:121], v[120:121], v[170:171], v[132:133] op_sel_hi:[1,0,1]
	v_pk_fma_f32 v[116:117], v[116:117], v[170:171], v[128:129] op_sel_hi:[1,0,1]
	v_pk_fma_f32 v[118:119], v[118:119], v[170:171], v[130:131] op_sel_hi:[1,0,1]
	v_pk_mul_f32 v[170:171], v[136:137], s[72:73] op_sel_hi:[1,0]
	v_pk_mul_f32 v[172:173], v[138:139], s[72:73] op_sel_hi:[1,0]
	v_pk_mul_f32 v[122:123], v[138:139], v[122:123]
	v_pk_mul_f32 v[138:139], v[126:127], s[72:73] op_sel_hi:[1,0]
	v_exp_f32_e32 v170, v170
	v_exp_f32_e32 v171, v171
	v_exp_f32_e32 v172, v172
	v_exp_f32_e32 v173, v173
	v_pk_mul_f32 v[120:121], v[136:137], v[120:121]
	v_pk_mul_f32 v[136:137], v[124:125], s[72:73] op_sel_hi:[1,0]
	v_exp_f32_e32 v138, v138
	v_exp_f32_e32 v139, v139
	v_exp_f32_e32 v136, v136
	v_exp_f32_e32 v137, v137
	v_pk_add_f32 v[170:171], v[170:171], 1.0 op_sel_hi:[1,0]
	v_pk_add_f32 v[172:173], v[172:173], 1.0 op_sel_hi:[1,0]
	v_pk_add_f32 v[138:139], v[138:139], 1.0 op_sel_hi:[1,0]
	v_rcp_f32_e32 v170, v170
	v_rcp_f32_e32 v171, v171
	v_rcp_f32_e32 v172, v172
	v_rcp_f32_e32 v173, v173
	v_pk_add_f32 v[136:137], v[136:137], 1.0 op_sel_hi:[1,0]
	v_rcp_f32_e32 v138, v138
	v_rcp_f32_e32 v139, v139
	v_rcp_f32_e32 v136, v136
	v_rcp_f32_e32 v137, v137
	v_pk_mul_f32 v[118:119], v[126:127], v[118:119]
	v_pk_mul_f32 v[120:121], v[120:121], v[170:171]
	v_pk_mul_f32 v[122:123], v[122:123], v[172:173]
	v_pk_mul_f32 v[116:117], v[124:125], v[116:117]
	v_pk_mul_f32 v[118:119], v[118:119], v[138:139]
	v_pk_mul_f32 v[116:117], v[116:117], v[136:137]
	v_cvt_pk_bf16_f32 v120, v120, v121
	v_cvt_pk_bf16_f32 v121, v122, v123
	s_nop 0
	v_cvt_pk_bf16_f32 v122, v116, v117
	v_cvt_pk_bf16_f32 v123, v118, v119
	ds_read_b32 v118, v163 offset:64
	v_mov_b64_e32 v[116:117], s[92:93]
	v_mad_i64_i32 v[124:125], s[22:23], v166, s34, v[116:117]
	s_waitcnt lgkmcnt(0)
	v_fmamk_f32 v118, v118, 0x3a000000, v233
	v_rsq_f32_e32 v126, v118
	v_lshlrev_b64 v[118:119], 1, v[168:169]
	v_lshl_add_u64 v[124:125], v[124:125], 0, v[118:119]
	global_store_dwordx4 v[124:125], v[120:123], off
	v_pk_fma_f32 v[112:113], v[112:113], v[126:127], v[144:145] op_sel_hi:[1,0,1]
	v_pk_fma_f32 v[114:115], v[114:115], v[126:127], v[146:147] op_sel_hi:[1,0,1]
	v_pk_fma_f32 v[110:111], v[110:111], v[126:127], v[142:143] op_sel_hi:[1,0,1]
	v_pk_fma_f32 v[108:109], v[108:109], v[126:127], v[140:141] op_sel_hi:[1,0,1]
	v_pk_fma_f32 v[104:105], v[104:105], v[126:127], v[132:133] op_sel_hi:[1,0,1]
	v_pk_fma_f32 v[106:107], v[106:107], v[126:127], v[134:135] op_sel_hi:[1,0,1]
	v_pk_mul_f32 v[120:121], v[112:113], s[72:73] op_sel_hi:[1,0]
	v_pk_mul_f32 v[122:123], v[114:115], s[72:73] op_sel_hi:[1,0]
	v_exp_f32_e32 v120, v120
	v_exp_f32_e32 v121, v121
	v_pk_mul_f32 v[106:107], v[114:115], v[106:107]
	v_pk_mul_f32 v[104:105], v[112:113], v[104:105]
	v_pk_mul_f32 v[112:113], v[108:109], s[72:73] op_sel_hi:[1,0]
	v_pk_mul_f32 v[114:115], v[110:111], s[72:73] op_sel_hi:[1,0]
	v_exp_f32_e32 v122, v122
	v_exp_f32_e32 v123, v123
	v_exp_f32_e32 v112, v112
	v_exp_f32_e32 v113, v113
	v_exp_f32_e32 v114, v114
	v_exp_f32_e32 v115, v115
	v_pk_add_f32 v[120:121], v[120:121], 1.0 op_sel_hi:[1,0]
	v_pk_add_f32 v[122:123], v[122:123], 1.0 op_sel_hi:[1,0]
	v_rcp_f32_e32 v120, v120
	v_rcp_f32_e32 v121, v121
	v_pk_add_f32 v[112:113], v[112:113], 1.0 op_sel_hi:[1,0]
	v_pk_add_f32 v[114:115], v[114:115], 1.0 op_sel_hi:[1,0]
	v_rcp_f32_e32 v122, v122
	v_rcp_f32_e32 v123, v123
	v_rcp_f32_e32 v112, v112
	v_rcp_f32_e32 v113, v113
	v_rcp_f32_e32 v114, v114
	v_rcp_f32_e32 v115, v115
	v_pk_fma_f32 v[100:101], v[100:101], v[126:127], v[128:129] op_sel_hi:[1,0,1]
	v_pk_fma_f32 v[102:103], v[102:103], v[126:127], v[130:131] op_sel_hi:[1,0,1]
	v_pk_mul_f32 v[104:105], v[104:105], v[120:121]
	v_pk_mul_f32 v[102:103], v[110:111], v[102:103]
	v_pk_mul_f32 v[100:101], v[108:109], v[100:101]
	v_pk_mul_f32 v[106:107], v[106:107], v[122:123]
	v_pk_mul_f32 v[108:109], v[100:101], v[112:113]
	v_pk_mul_f32 v[110:111], v[102:103], v[114:115]
	v_cvt_pk_bf16_f32 v100, v104, v105
	v_cvt_pk_bf16_f32 v101, v106, v107
	v_cvt_pk_bf16_f32 v102, v108, v109
	v_or_b32_e32 v105, 16, v166
	v_cvt_pk_bf16_f32 v103, v110, v111
	ds_read_b32 v104, v163 offset:128
	v_mad_i64_i32 v[106:107], s[22:23], v105, s34, v[116:117]
	v_lshl_add_u64 v[106:107], v[106:107], 0, v[118:119]
	global_store_dwordx4 v[106:107], v[100:103], off
	s_waitcnt lgkmcnt(0)
; __device__ __forceinline__ unsigned cvt_pk_bf16(float lo, float hi) { unsigned r; asm volatile("v_cvt_pk_bf16_f32 %0, %1, %2" : "=v"(r) : "v"(lo), "v"(hi)); return r; }
;     __device__ __forceinline__ void operator()(const f32x4 (&acc)[2][2][4][2], const Unit& u, int wr, int wc, int fr, int fq, PG8_LAS unsigned char* sl) const {
;     ...
;             for (int m = 0; m < 4; ++m) { const int row = row0 + ai * HALF + m * 16; bf16_t* rowp = O + (size_t)row * ldc + col0;
;                 const float rs = __builtin_amdgcn_rsqf(sf[ai * 64 + m * 16 + fr] * (1.0f / 2048.0f) + 1e-6f);
;                 const f32x4 a0 = acc[ai][0][m][0] * rs + bw[0][0], a1 = acc[ai][0][m][1] * rs + bw[0][1], b0 = acc[ai][1][m][0] * rs + bw[1][0], b1 = acc[ai][1][m][1] * rs + bw[1][1];
;                 const f32x2 s0 = silu_mul_pk((f32x2){a0[0], a0[1]}, (f32x2){b0[0], b0[1]}), s1 = silu_mul_pk((f32x2){a0[2], a0[3]}, (f32x2){b0[2], b0[3]});
;                 const f32x2 s2 = silu_mul_pk((f32x2){a1[0], a1[1]}, (f32x2){b1[0], b1[1]}), s3 = silu_mul_pk((f32x2){a1[2], a1[3]}, (f32x2){b1[2], b1[3]});
;                 u32x4 w; w.x = cvt_pk_bf16(s0.x, s0.y); w.y = cvt_pk_bf16(s1.x, s1.y); w.z = cvt_pk_bf16(s2.x, s2.y); w.w = cvt_pk_bf16(s3.x, s3.y);
;                 *(u32x4*)rowp = w; }
	v_fmamk_f32 v104, v104, 0x3a000000, v233
	v_rsq_f32_e32 v104, v104
	s_nop 0
	v_pk_fma_f32 v[96:97], v[96:97], v[104:105], v[144:145] op_sel_hi:[1,0,1]
	v_pk_fma_f32 v[98:99], v[98:99], v[104:105], v[146:147] op_sel_hi:[1,0,1]
	v_pk_fma_f32 v[94:95], v[94:95], v[104:105], v[142:143] op_sel_hi:[1,0,1]
	v_pk_fma_f32 v[92:93], v[92:93], v[104:105], v[140:141] op_sel_hi:[1,0,1]
	v_pk_fma_f32 v[88:89], v[88:89], v[104:105], v[132:133] op_sel_hi:[1,0,1]
	v_pk_fma_f32 v[90:91], v[90:91], v[104:105], v[134:135] op_sel_hi:[1,0,1]
	v_pk_mul_f32 v[100:101], v[96:97], s[72:73] op_sel_hi:[1,0]
	v_pk_mul_f32 v[102:103], v[98:99], s[72:73] op_sel_hi:[1,0]
	v_exp_f32_e32 v100, v100
	v_exp_f32_e32 v101, v101
	v_pk_mul_f32 v[90:91], v[98:99], v[90:91]
	v_pk_mul_f32 v[88:89], v[96:97], v[88:89]
	v_pk_mul_f32 v[96:97], v[92:93], s[72:73] op_sel_hi:[1,0]
	v_pk_mul_f32 v[98:99], v[94:95], s[72:73] op_sel_hi:[1,0]
	v_exp_f32_e32 v102, v102
	v_exp_f32_e32 v103, v103
	v_exp_f32_e32 v96, v96
	v_exp_f32_e32 v97, v97
	v_exp_f32_e32 v98, v98
	v_exp_f32_e32 v99, v99
	v_pk_add_f32 v[100:101], v[100:101], 1.0 op_sel_hi:[1,0]
	v_pk_add_f32 v[102:103], v[102:103], 1.0 op_sel_hi:[1,0]
	v_rcp_f32_e32 v100, v100
	v_rcp_f32_e32 v101, v101
	v_pk_add_f32 v[96:97], v[96:97], 1.0 op_sel_hi:[1,0]
	v_pk_add_f32 v[98:99], v[98:99], 1.0 op_sel_hi:[1,0]
	v_rcp_f32_e32 v102, v102
	v_rcp_f32_e32 v103, v103
	v_rcp_f32_e32 v96, v96
	v_rcp_f32_e32 v97, v97
	v_rcp_f32_e32 v98, v98
	v_rcp_f32_e32 v99, v99
	v_pk_fma_f32 v[84:85], v[84:85], v[104:105], v[128:129] op_sel_hi:[1,0,1]
	v_pk_fma_f32 v[86:87], v[86:87], v[104:105], v[130:131] op_sel_hi:[1,0,1]
	v_pk_mul_f32 v[88:89], v[88:89], v[100:101]
	v_pk_mul_f32 v[86:87], v[94:95], v[86:87]
	v_pk_mul_f32 v[84:85], v[92:93], v[84:85]
	v_pk_mul_f32 v[90:91], v[90:91], v[102:103]
	v_pk_mul_f32 v[92:93], v[84:85], v[96:97]
	v_pk_mul_f32 v[94:95], v[86:87], v[98:99]
	v_cvt_pk_bf16_f32 v84, v88, v89
	v_cvt_pk_bf16_f32 v85, v90, v91
	v_cvt_pk_bf16_f32 v86, v92, v93
	v_or_b32_e32 v89, 32, v166
	v_cvt_pk_bf16_f32 v87, v94, v95
	ds_read_b32 v88, v163 offset:192
	v_mad_i64_i32 v[90:91], s[22:23], v89, s34, v[116:117]
	v_lshl_add_u64 v[90:91], v[90:91], 0, v[118:119]
	global_store_dwordx4 v[90:91], v[84:87], off
	s_waitcnt lgkmcnt(0)
	v_fmamk_f32 v88, v88, 0x3a000000, v233
	v_rsq_f32_e32 v88, v88
	s_nop 0
	v_pk_fma_f32 v[80:81], v[80:81], v[88:89], v[144:145] op_sel_hi:[1,0,1]
	v_pk_fma_f32 v[82:83], v[82:83], v[88:89], v[146:147] op_sel_hi:[1,0,1]
	v_pk_fma_f32 v[78:79], v[78:79], v[88:89], v[142:143] op_sel_hi:[1,0,1]
	v_pk_fma_f32 v[76:77], v[76:77], v[88:89], v[140:141] op_sel_hi:[1,0,1]
	v_pk_fma_f32 v[72:73], v[72:73], v[88:89], v[132:133] op_sel_hi:[1,0,1]
	v_pk_fma_f32 v[74:75], v[74:75], v[88:89], v[134:135] op_sel_hi:[1,0,1]
	v_pk_mul_f32 v[84:85], v[80:81], s[72:73] op_sel_hi:[1,0]
	v_pk_mul_f32 v[86:87], v[82:83], s[72:73] op_sel_hi:[1,0]
	v_exp_f32_e32 v84, v84
	v_exp_f32_e32 v85, v85
	v_pk_mul_f32 v[74:75], v[82:83], v[74:75]
	v_pk_mul_f32 v[72:73], v[80:81], v[72:73]
	v_pk_mul_f32 v[80:81], v[76:77], s[72:73] op_sel_hi:[1,0]
	v_pk_mul_f32 v[82:83], v[78:79], s[72:73] op_sel_hi:[1,0]
	v_exp_f32_e32 v86, v86
	v_exp_f32_e32 v87, v87
	v_exp_f32_e32 v80, v80
	v_exp_f32_e32 v81, v81
	v_exp_f32_e32 v82, v82
	v_exp_f32_e32 v83, v83
	v_pk_add_f32 v[84:85], v[84:85], 1.0 op_sel_hi:[1,0]
	v_pk_add_f32 v[86:87], v[86:87], 1.0 op_sel_hi:[1,0]
	v_rcp_f32_e32 v84, v84
	v_rcp_f32_e32 v85, v85
	v_pk_add_f32 v[80:81], v[80:81], 1.0 op_sel_hi:[1,0]
	v_pk_add_f32 v[82:83], v[82:83], 1.0 op_sel_hi:[1,0]
	v_rcp_f32_e32 v86, v86
	v_rcp_f32_e32 v87, v87
	v_rcp_f32_e32 v80, v80
	v_rcp_f32_e32 v81, v81
	v_rcp_f32_e32 v82, v82
	v_rcp_f32_e32 v83, v83
	v_pk_fma_f32 v[68:69], v[68:69], v[88:89], v[128:129] op_sel_hi:[1,0,1]
	v_pk_fma_f32 v[70:71], v[70:71], v[88:89], v[130:131] op_sel_hi:[1,0,1]
	v_pk_mul_f32 v[72:73], v[72:73], v[84:85]
	v_pk_mul_f32 v[70:71], v[78:79], v[70:71]
	v_pk_mul_f32 v[68:69], v[76:77], v[68:69]
	v_pk_mul_f32 v[74:75], v[74:75], v[86:87]
	v_pk_mul_f32 v[76:77], v[68:69], v[80:81]
	v_pk_mul_f32 v[78:79], v[70:71], v[82:83]
	v_cvt_pk_bf16_f32 v68, v72, v73
	v_cvt_pk_bf16_f32 v69, v74, v75
	v_cvt_pk_bf16_f32 v70, v76, v77
	v_or_b32_e32 v73, 48, v166
	v_cvt_pk_bf16_f32 v71, v78, v79
	ds_read_b32 v72, v163 offset:256
	v_mad_i64_i32 v[74:75], s[22:23], v73, s34, v[116:117]
	v_lshl_add_u64 v[74:75], v[74:75], 0, v[118:119]
	global_store_dwordx4 v[74:75], v[68:71], off
	s_waitcnt lgkmcnt(0)
	v_fmamk_f32 v72, v72, 0x3a000000, v233
	v_rsq_f32_e32 v72, v72
	s_nop 0
	v_pk_fma_f32 v[64:65], v[64:65], v[72:73], v[144:145] op_sel_hi:[1,0,1]
	v_pk_fma_f32 v[66:67], v[66:67], v[72:73], v[146:147] op_sel_hi:[1,0,1]
	v_pk_fma_f32 v[62:63], v[62:63], v[72:73], v[142:143] op_sel_hi:[1,0,1]
	v_pk_fma_f32 v[60:61], v[60:61], v[72:73], v[140:141] op_sel_hi:[1,0,1]
	v_pk_fma_f32 v[56:57], v[56:57], v[72:73], v[132:133] op_sel_hi:[1,0,1]
	v_pk_fma_f32 v[58:59], v[58:59], v[72:73], v[134:135] op_sel_hi:[1,0,1]
	v_pk_mul_f32 v[68:69], v[64:65], s[72:73] op_sel_hi:[1,0]
	v_pk_mul_f32 v[70:71], v[66:67], s[72:73] op_sel_hi:[1,0]
	v_exp_f32_e32 v68, v68
	v_exp_f32_e32 v69, v69
	v_pk_mul_f32 v[58:59], v[66:67], v[58:59]
	v_pk_mul_f32 v[56:57], v[64:65], v[56:57]
	v_pk_mul_f32 v[64:65], v[60:61], s[72:73] op_sel_hi:[1,0]
	v_pk_mul_f32 v[66:67], v[62:63], s[72:73] op_sel_hi:[1,0]
	v_exp_f32_e32 v70, v70
	v_exp_f32_e32 v71, v71
	v_exp_f32_e32 v64, v64
	v_exp_f32_e32 v65, v65
	v_exp_f32_e32 v66, v66
	v_exp_f32_e32 v67, v67
	v_pk_add_f32 v[68:69], v[68:69], 1.0 op_sel_hi:[1,0]
	v_pk_add_f32 v[70:71], v[70:71], 1.0 op_sel_hi:[1,0]
	v_rcp_f32_e32 v68, v68
	v_rcp_f32_e32 v69, v69
	v_pk_add_f32 v[64:65], v[64:65], 1.0 op_sel_hi:[1,0]
	v_pk_add_f32 v[66:67], v[66:67], 1.0 op_sel_hi:[1,0]
	v_rcp_f32_e32 v70, v70
	v_rcp_f32_e32 v71, v71
	v_rcp_f32_e32 v64, v64
	v_rcp_f32_e32 v65, v65
	v_rcp_f32_e32 v66, v66
	v_rcp_f32_e32 v67, v67
	v_pk_fma_f32 v[52:53], v[52:53], v[72:73], v[128:129] op_sel_hi:[1,0,1]
	v_pk_fma_f32 v[54:55], v[54:55], v[72:73], v[130:131] op_sel_hi:[1,0,1]
	v_pk_mul_f32 v[56:57], v[56:57], v[68:69]
	v_pk_mul_f32 v[54:55], v[62:63], v[54:55]
	v_pk_mul_f32 v[52:53], v[60:61], v[52:53]
	v_pk_mul_f32 v[58:59], v[58:59], v[70:71]
	v_pk_mul_f32 v[60:61], v[52:53], v[64:65]
	v_pk_mul_f32 v[62:63], v[54:55], v[66:67]
	v_cvt_pk_bf16_f32 v52, v56, v57
	v_cvt_pk_bf16_f32 v53, v58, v59
	v_cvt_pk_bf16_f32 v54, v60, v61
	v_add_u32_e32 v57, 0x80, v166
	v_cvt_pk_bf16_f32 v55, v62, v63
	ds_read_b32 v56, v163 offset:320
	v_mad_i64_i32 v[58:59], s[22:23], v57, s34, v[116:117]
	v_lshl_add_u64 v[58:59], v[58:59], 0, v[118:119]
	global_store_dwordx4 v[58:59], v[52:55], off
	s_waitcnt lgkmcnt(0)
; __device__ __forceinline__ unsigned cvt_pk_bf16(float lo, float hi) { unsigned r; asm volatile("v_cvt_pk_bf16_f32 %0, %1, %2" : "=v"(r) : "v"(lo), "v"(hi)); return r; }
; #define PG8_BAR __builtin_amdgcn_s_barrier()
;     __device__ __forceinline__ void operator()(const f32x4 (&acc)[2][2][4][2], const Unit& u, int wr, int wc, int fr, int fq, PG8_LAS unsigned char* sl) const {
;     ...
;             for (int m = 0; m < 4; ++m) { const int row = row0 + ai * HALF + m * 16; bf16_t* rowp = O + (size_t)row * ldc + col0;
;                 const float rs = __builtin_amdgcn_rsqf(sf[ai * 64 + m * 16 + fr] * (1.0f / 2048.0f) + 1e-6f);
;                 const f32x4 a0 = acc[ai][0][m][0] * rs + bw[0][0], a1 = acc[ai][0][m][1] * rs + bw[0][1], b0 = acc[ai][1][m][0] * rs + bw[1][0], b1 = acc[ai][1][m][1] * rs + bw[1][1];
;                 const f32x2 s0 = silu_mul_pk((f32x2){a0[0], a0[1]}, (f32x2){b0[0], b0[1]}), s1 = silu_mul_pk((f32x2){a0[2], a0[3]}, (f32x2){b0[2], b0[3]});
;                 const f32x2 s2 = silu_mul_pk((f32x2){a1[0], a1[1]}, (f32x2){b1[0], b1[1]}), s3 = silu_mul_pk((f32x2){a1[2], a1[3]}, (f32x2){b1[2], b1[3]});
;                 u32x4 w; w.x = cvt_pk_bf16(s0.x, s0.y); w.y = cvt_pk_bf16(s1.x, s1.y); w.z = cvt_pk_bf16(s2.x, s2.y); w.w = cvt_pk_bf16(s3.x, s3.y);
;                 *(u32x4*)rowp = w; }
; template <class Epi, class Sched, bool ALIGN_EPI = false, bool SP2 = false>
; __device__ __forceinline__ void gemm_phase(PG8_LAS unsigned char* lds, const Gemm g, const Sched& S, const Epi& E, const int tid) {
;     ...
;         if (!has_next) break;
; #pragma unroll
;         for (int a = 0; a < 2; ++a)
; #pragma unroll
;             for (int b = 0; b < 2; ++b)
; #pragma unroll
;                 for (int m = 0; m < 4; ++m)
; #pragma unroll
;                     for (int n = 0; n < 2; ++n) acc[a][b][m][n] = (f32x4){0.f, 0.f, 0.f, 0.f};
;         cur = nxt; cA = nA; cB = nB; ++ui;
;         if constexpr (ALIGN_EPI) { if (wr == 1) PG8_BAR; }
	v_fmamk_f32 v56, v56, 0x3a000000, v233
	v_rsq_f32_e32 v56, v56
	s_nop 0
	v_pk_fma_f32 v[48:49], v[48:49], v[56:57], v[144:145] op_sel_hi:[1,0,1]
	v_pk_fma_f32 v[50:51], v[50:51], v[56:57], v[146:147] op_sel_hi:[1,0,1]
	v_pk_fma_f32 v[46:47], v[46:47], v[56:57], v[142:143] op_sel_hi:[1,0,1]
	v_pk_fma_f32 v[44:45], v[44:45], v[56:57], v[140:141] op_sel_hi:[1,0,1]
	v_pk_fma_f32 v[40:41], v[40:41], v[56:57], v[132:133] op_sel_hi:[1,0,1]
	v_pk_fma_f32 v[42:43], v[42:43], v[56:57], v[134:135] op_sel_hi:[1,0,1]
	v_pk_mul_f32 v[52:53], v[48:49], s[72:73] op_sel_hi:[1,0]
	v_pk_mul_f32 v[54:55], v[50:51], s[72:73] op_sel_hi:[1,0]
	v_exp_f32_e32 v52, v52
	v_exp_f32_e32 v53, v53
	v_pk_mul_f32 v[42:43], v[50:51], v[42:43]
	v_pk_mul_f32 v[40:41], v[48:49], v[40:41]
	v_pk_mul_f32 v[48:49], v[44:45], s[72:73] op_sel_hi:[1,0]
	v_pk_mul_f32 v[50:51], v[46:47], s[72:73] op_sel_hi:[1,0]
	v_exp_f32_e32 v54, v54
	v_exp_f32_e32 v55, v55
	v_exp_f32_e32 v48, v48
	v_exp_f32_e32 v49, v49
	v_exp_f32_e32 v50, v50
	v_exp_f32_e32 v51, v51
	v_pk_add_f32 v[52:53], v[52:53], 1.0 op_sel_hi:[1,0]
	v_pk_add_f32 v[54:55], v[54:55], 1.0 op_sel_hi:[1,0]
	v_rcp_f32_e32 v52, v52
	v_rcp_f32_e32 v53, v53
	v_pk_add_f32 v[48:49], v[48:49], 1.0 op_sel_hi:[1,0]
	v_pk_add_f32 v[50:51], v[50:51], 1.0 op_sel_hi:[1,0]
	v_rcp_f32_e32 v54, v54
	v_rcp_f32_e32 v55, v55
	v_rcp_f32_e32 v48, v48
	v_rcp_f32_e32 v49, v49
	v_rcp_f32_e32 v50, v50
	v_rcp_f32_e32 v51, v51
	v_pk_fma_f32 v[36:37], v[36:37], v[56:57], v[128:129] op_sel_hi:[1,0,1]
	v_pk_fma_f32 v[38:39], v[38:39], v[56:57], v[130:131] op_sel_hi:[1,0,1]
	v_pk_mul_f32 v[40:41], v[40:41], v[52:53]
	v_pk_mul_f32 v[38:39], v[46:47], v[38:39]
	v_pk_mul_f32 v[36:37], v[44:45], v[36:37]
	v_pk_mul_f32 v[42:43], v[42:43], v[54:55]
	v_pk_mul_f32 v[44:45], v[36:37], v[48:49]
	v_pk_mul_f32 v[46:47], v[38:39], v[50:51]
	v_cvt_pk_bf16_f32 v36, v40, v41
	v_cvt_pk_bf16_f32 v37, v42, v43
	v_cvt_pk_bf16_f32 v38, v44, v45
	v_add_u32_e32 v41, 0x90, v166
	v_cvt_pk_bf16_f32 v39, v46, v47
	ds_read_b32 v40, v163 offset:384
	v_mad_i64_i32 v[42:43], s[22:23], v41, s34, v[116:117]
	v_lshl_add_u64 v[42:43], v[42:43], 0, v[118:119]
	global_store_dwordx4 v[42:43], v[36:39], off
	s_waitcnt lgkmcnt(0)
	v_fmamk_f32 v40, v40, 0x3a000000, v233
	v_rsq_f32_e32 v40, v40
	v_add_u32_e32 v44, 0xa0, v166
	v_add_u32_e32 v45, 0xb0, v166
	v_pk_fma_f32 v[34:35], v[34:35], v[40:41], v[146:147] op_sel_hi:[1,0,1]
	v_pk_fma_f32 v[32:33], v[32:33], v[40:41], v[144:145] op_sel_hi:[1,0,1]
	v_pk_fma_f32 v[30:31], v[30:31], v[40:41], v[142:143] op_sel_hi:[1,0,1]
	v_pk_fma_f32 v[28:29], v[28:29], v[40:41], v[140:141] op_sel_hi:[1,0,1]
	v_pk_fma_f32 v[24:25], v[24:25], v[40:41], v[132:133] op_sel_hi:[1,0,1]
	v_pk_fma_f32 v[26:27], v[26:27], v[40:41], v[134:135] op_sel_hi:[1,0,1]
	v_pk_mul_f32 v[38:39], v[34:35], s[72:73] op_sel_hi:[1,0]
	v_pk_mul_f32 v[36:37], v[32:33], s[72:73] op_sel_hi:[1,0]
	v_exp_f32_e32 v38, v38
	v_exp_f32_e32 v39, v39
	v_pk_mul_f32 v[26:27], v[34:35], v[26:27]
	v_pk_mul_f32 v[24:25], v[32:33], v[24:25]
	v_pk_mul_f32 v[32:33], v[28:29], s[72:73] op_sel_hi:[1,0]
	v_pk_mul_f32 v[34:35], v[30:31], s[72:73] op_sel_hi:[1,0]
	v_exp_f32_e32 v36, v36
	v_exp_f32_e32 v37, v37
	v_exp_f32_e32 v32, v32
	v_exp_f32_e32 v33, v33
	v_exp_f32_e32 v34, v34
	v_exp_f32_e32 v35, v35
	v_pk_add_f32 v[38:39], v[38:39], 1.0 op_sel_hi:[1,0]
	v_pk_add_f32 v[36:37], v[36:37], 1.0 op_sel_hi:[1,0]
	v_rcp_f32_e32 v38, v38
	v_rcp_f32_e32 v39, v39
	v_pk_add_f32 v[32:33], v[32:33], 1.0 op_sel_hi:[1,0]
	v_pk_add_f32 v[34:35], v[34:35], 1.0 op_sel_hi:[1,0]
	v_rcp_f32_e32 v36, v36
	v_rcp_f32_e32 v37, v37
	v_rcp_f32_e32 v32, v32
	v_rcp_f32_e32 v33, v33
	v_rcp_f32_e32 v34, v34
	v_rcp_f32_e32 v35, v35
	v_pk_fma_f32 v[20:21], v[20:21], v[40:41], v[128:129] op_sel_hi:[1,0,1]
	v_pk_fma_f32 v[22:23], v[22:23], v[40:41], v[130:131] op_sel_hi:[1,0,1]
	v_pk_mul_f32 v[26:27], v[26:27], v[38:39]
	v_pk_mul_f32 v[22:23], v[30:31], v[22:23]
	v_pk_mul_f32 v[20:21], v[28:29], v[20:21]
	v_pk_mul_f32 v[24:25], v[24:25], v[36:37]
	v_pk_mul_f32 v[28:29], v[20:21], v[32:33]
	v_pk_mul_f32 v[30:31], v[22:23], v[34:35]
	v_cvt_pk_bf16_f32 v20, v24, v25
	v_cvt_pk_bf16_f32 v21, v26, v27
	v_cvt_pk_bf16_f32 v22, v28, v29
	v_mad_i64_i32 v[24:25], s[22:23], v44, s34, v[116:117]
	v_cvt_pk_bf16_f32 v23, v30, v31
	ds_read_b32 v26, v163 offset:448
	v_lshl_add_u64 v[24:25], v[24:25], 0, v[118:119]
	global_store_dwordx4 v[24:25], v[20:23], off
	s_waitcnt lgkmcnt(0)
	s_nop 0
	v_fmamk_f32 v20, v26, 0x3a000000, v233
	v_rsq_f32_e32 v20, v20
	v_mad_i64_i32 v[22:23], s[22:23], v45, s34, v[116:117]
	v_lshl_add_u64 v[22:23], v[22:23], 0, v[118:119]
	v_pk_fma_f32 v[18:19], v[18:19], v[20:21], v[146:147] op_sel_hi:[1,0,1]
	v_pk_fma_f32 v[16:17], v[16:17], v[20:21], v[144:145] op_sel_hi:[1,0,1]
	v_pk_fma_f32 v[14:15], v[14:15], v[20:21], v[142:143] op_sel_hi:[1,0,1]
	v_pk_fma_f32 v[12:13], v[12:13], v[20:21], v[140:141] op_sel_hi:[1,0,1]
	v_pk_fma_f32 v[8:9], v[8:9], v[20:21], v[132:133] op_sel_hi:[1,0,1]
	v_pk_fma_f32 v[10:11], v[10:11], v[20:21], v[134:135] op_sel_hi:[1,0,1]
	v_pk_fma_f32 v[4:5], v[4:5], v[20:21], v[128:129] op_sel_hi:[1,0,1]
	v_pk_fma_f32 v[6:7], v[6:7], v[20:21], v[130:131] op_sel_hi:[1,0,1]
	v_pk_mul_f32 v[20:21], v[16:17], s[72:73] op_sel_hi:[1,0]
	v_pk_mul_f32 v[24:25], v[18:19], s[72:73] op_sel_hi:[1,0]
	v_pk_mul_f32 v[10:11], v[18:19], v[10:11]
	v_pk_mul_f32 v[8:9], v[16:17], v[8:9]
	v_pk_mul_f32 v[16:17], v[12:13], s[72:73] op_sel_hi:[1,0]
	v_pk_mul_f32 v[18:19], v[14:15], s[72:73] op_sel_hi:[1,0]
	v_exp_f32_e32 v20, v20
	v_exp_f32_e32 v21, v21
	v_exp_f32_e32 v24, v24
	v_exp_f32_e32 v25, v25
	v_exp_f32_e32 v16, v16
	v_exp_f32_e32 v17, v17
	v_exp_f32_e32 v18, v18
	v_exp_f32_e32 v19, v19
	v_pk_add_f32 v[20:21], v[20:21], 1.0 op_sel_hi:[1,0]
	v_pk_add_f32 v[24:25], v[24:25], 1.0 op_sel_hi:[1,0]
	v_pk_add_f32 v[16:17], v[16:17], 1.0 op_sel_hi:[1,0]
	v_pk_add_f32 v[18:19], v[18:19], 1.0 op_sel_hi:[1,0]
	v_rcp_f32_e32 v20, v20
	v_rcp_f32_e32 v21, v21
	v_rcp_f32_e32 v24, v24
	v_rcp_f32_e32 v25, v25
	v_rcp_f32_e32 v16, v16
	v_rcp_f32_e32 v17, v17
	v_rcp_f32_e32 v18, v18
	v_rcp_f32_e32 v19, v19
	v_pk_mul_f32 v[6:7], v[14:15], v[6:7]
	v_pk_mul_f32 v[4:5], v[12:13], v[4:5]
	v_pk_mul_f32 v[8:9], v[8:9], v[20:21]
	v_pk_mul_f32 v[10:11], v[10:11], v[24:25]
	v_pk_mul_f32 v[12:13], v[4:5], v[16:17]
	v_pk_mul_f32 v[14:15], v[6:7], v[18:19]
	v_cvt_pk_bf16_f32 v4, v8, v9
	v_cvt_pk_bf16_f32 v5, v10, v11
	v_cvt_pk_bf16_f32 v6, v12, v13
	s_nop 0
	v_cvt_pk_bf16_f32 v7, v14, v15
	global_store_dwordx4 v[22:23], v[4:7], off
	s_cbranch_vccnz .LBB0_262
	s_andn2_b64 vcc, exec, s[10:11]
	s_cbranch_vccnz .LBB0_261
	s_barrier
	s_branch .LBB0_261
